# grid barrier: globally-last XCD leader bumps all 16 XGEN words directly, per-leader XGEN bump removed (one release hop fewer)
# speedup vs baseline: 1.0044x; 1.0044x over previous
.LBB0_960:
	s_or_b64 exec, exec, s[6:7]
	s_waitcnt vmcnt(0)
	v_readfirstlane_b32 s4, v3
	v_sub_u32_e32 v4, 0, v2
	s_mov_b64 s[8:9], -1
	v_add_u32_e32 v3, s4, v0
	v_cvt_f32_u32_e32 v0, v2
	s_add_u32 s4, s54, 0x1efc3500
	s_addc_u32 s5, s55, 0
	v_rcp_iflag_f32_e32 v0, v0
	s_nop 0
	v_mul_f32_e32 v0, 0x4f7ffffe, v0
	v_cvt_u32_f32_e32 v0, v0
	v_mul_lo_u32 v4, v4, v0
	v_mul_hi_u32 v4, v0, v4
	v_add_u32_e32 v0, v0, v4
	v_mul_hi_u32 v0, v3, v0
	v_mul_lo_u32 v4, v0, v2
	v_sub_u32_e32 v4, v3, v4
	v_cmp_ge_u32_e32 vcc, v4, v2
	v_add_u32_e32 v5, 1, v0
	v_add_u32_e32 v3, 1, v3
	v_cndmask_b32_e32 v0, v0, v5, vcc
	v_sub_u32_e32 v5, v4, v2
	v_cndmask_b32_e32 v4, v4, v5, vcc
	v_cmp_ge_u32_e32 vcc, v4, v2
	v_add_u32_e32 v4, 1, v0
	s_nop 0
	v_cndmask_b32_e32 v0, v0, v4, vcc
	v_mul_lo_u32 v4, v2, v0
	v_add_u32_e32 v2, v4, v2
	v_cmp_ne_u32_e32 vcc, v3, v2
	s_cbranch_vccnz .Lxb_notlast
	v_mov_b32_e32 v6, 0x1efc2c00
	global_atomic_add v6, v212, s[54:55] offset:-2048
	global_atomic_add v6, v212, s[54:55] offset:-1792
	global_atomic_add v6, v212, s[54:55] offset:-1536
	global_atomic_add v6, v212, s[54:55] offset:-1280
	global_atomic_add v6, v212, s[54:55] offset:-1024
	global_atomic_add v6, v212, s[54:55] offset:-768
	global_atomic_add v6, v212, s[54:55] offset:-512
	global_atomic_add v6, v212, s[54:55] offset:-256
	global_atomic_add v6, v212, s[54:55]
	global_atomic_add v6, v212, s[54:55] offset:256
	global_atomic_add v6, v212, s[54:55] offset:512
	global_atomic_add v6, v212, s[54:55] offset:768
	global_atomic_add v6, v212, s[54:55] offset:1024
	global_atomic_add v6, v212, s[54:55] offset:1280
	global_atomic_add v6, v212, s[54:55] offset:1536
	global_atomic_add v6, v212, s[54:55] offset:1792
.Lxb_notlast:
	v_mov_b64_e32 v[2:3], s[4:5]
	s_and_saveexec_b64 s[6:7], vcc
	s_cbranch_execz .LBB0_972
	global_load_dword v2, v1, s[4:5] sc1
	s_mov_b64 s[12:13], 0
	s_waitcnt vmcnt(0)
	v_cmp_eq_u32_e32 vcc, v2, v0
	s_and_saveexec_b64 s[10:11], vcc
	s_cbranch_execz .LBB0_971
	s_add_u32 s8, s54, 0x1efc0200
	s_addc_u32 s9, s55, 0
	s_mov_b32 s22, 1
	s_branch .LBB0_964

.LBB0_975:
	s_bcnt1_i32_b64 s4, s[4:5]
	v_mov_b32_e32 v0, s4
	s_getpc_b64 s[98:99]
